# G1 takes its unit table backwards (column segments gates..x_rnn, so the RNN inputs are the most recently written); v75 otherwise
# baseline (speedup 1.0000x reference)
.LBB0_201:
	s_cmp_gt_i32 s39, 0
	s_cselect_b64 s[18:19], -1, 0
	s_cmp_lt_i32 s39, 1
	s_cbranch_scc1 .LBB0_204
	s_add_i32 s4, 0, 0x20200
	s_add_i32 s99, s39, -1
	s_lshl_b32 s99, s99, 4
	s_add_i32 s4, s4, s99
	v_mov_b32_e32 v0, s4
	ds_read_b96 v[0:2], v0
	s_waitcnt lgkmcnt(0)
	v_readfirstlane_b32 s4, v2
	s_cmp_eq_u32 s4, 0
	v_readfirstlane_b32 s14, v0
	v_readfirstlane_b32 s16, v1
	s_cselect_b64 s[4:5], -1, 0
	s_andn2_b64 vcc, exec, s[18:19]
	s_cbranch_vccz .LBB0_205

.LBB0_210:
	s_add_i32 s44, s80, 1
	s_cmp_lt_i32 s44, s39
	s_cselect_b64 s[74:75], -1, 0
	s_cmp_ge_i32 s44, s39
	s_cbranch_scc1 .LBB0_212
	s_sub_i32 s15, s39, s44
	s_add_i32 s15, s15, -1
	s_lshl_b32 s15, s15, 4
	s_add_i32 s15, s15, 0
	s_add_i32 s15, s15, 0x20200
	v_mov_b32_e32 v0, s15
	ds_read_b96 v[0:2], v0
	s_waitcnt lgkmcnt(0)
	v_readfirstlane_b32 s64, v0
	v_readfirstlane_b32 s66, v1
	v_readfirstlane_b32 s29, v2
